# speedup vs baseline: 1.0101x; 1.0101x over previous
; __device__ __forceinline__ float bf2f(u16 h) { return __uint_as_float(((unsigned)h) << 16); }
; __device__ __forceinline__ float silu_f(float x) { return x / (1.f + __expf(-x)); }
; __device__ __forceinline__ void gla_out_job(const Params& p, int layer, int half, int job, char* smem) {
;     ...
;   {
;     const float* gn = p.gla_norm + layer * 64;
;     u16* y = p.xn;
;     float tot[4][4];
;     float ss[4] = {0.f, 0.f, 0.f, 0.f};
; #pragma unroll
;     for (int nt = 0; nt < 4; ++nt)
; #pragma unroll
;       for (int j = 0; j < 4; ++j) {
;         int prow = 63 - (wid * 16 + fq * 4 + j);
;         float t = acc[nt][j] + s_O[prow * 64 + nt * 16 + fr];
;         tot[nt][j] = t;
;         ss[j] += t * t;
;       }
; #pragma unroll
;     for (int j = 0; j < 4; ++j) {
;       float s = ss[j];
;       s += __shfl_xor(s, 1); s += __shfl_xor(s, 2); s += __shfl_xor(s, 4); s += __shfl_xor(s, 8);
;       ss[j] = rsqrtf(s * (1.f / 64.f) + 1e-6f);
;     }
; #pragma unroll
;     for (int nt = 0; nt < 4; ++nt) {
;       int v = nt * 16 + fr;
;       float gw = gn[v];
; #pragma unroll
;       for (int j = 0; j < 4; ++j) {
;         int prow = 63 - (wid * 16 + fq * 4 + j);
;         size_t tok = (size_t)(tok0 + prow);
;         float g = bf2f(proj[tok * PW + 512 + hd * 64 + v]);
;         y[tok * DM + hd * 64 + v] = f2bf(tot[nt][j] * ss[j] * gw * silu_f(g));
.LBB0_227:
	s_lshl_b32 s2, s83, 6
	s_ashr_i32 s3, s2, 31
	s_mov_b32 s6, 0x3fffff0
	v_mul_lo_u32 v36, v41, s6
	s_lshl_b64 s[2:3], s[2:3], 2
	v_readlane_b32 s6, v255, 25
	v_sub_u32_e32 v16, v36, v39
	v_readlane_b32 s7, v255, 26
	s_add_u32 s2, s6, s2
	v_lshlrev_b32_e32 v16, 8, v16
	s_addc_u32 s3, s7, s3
	s_or_b32 s6, s66, 63
	v_add3_u32 v16, s65, v16, v40
	v_sub_u32_e32 v26, s6, v25
	v_mov_b64_e32 v[22:23], s[62:63]
	v_add_u32_e32 v27, 0xf800, v16
	s_lshl_b32 s66, s82, 1
	v_mad_i64_i32 v[16:17], s[8:9], v26, s71, v[22:23]
	v_lshl_add_u64 v[16:17], v[16:17], 0, s[66:67]
	v_mov_b32_e32 v25, v199
	v_lshl_add_u64 v[16:17], v[16:17], 0, v[24:25]
	global_load_ushort v37, v[16:17], off offset:1024
	global_load_dword v42, v40, s[2:3]
	v_or_b32_e32 v43, 1, v39
	v_sub_u32_e32 v20, v36, v43
	v_lshlrev_b32_e32 v20, 8, v20
	v_add3_u32 v20, s65, v20, v40
	v_add_u32_e32 v32, 0xf800, v20
	ds_read2_b32 v[18:19], v27 offset1:16
	ds_read2_b32 v[28:29], v32 offset1:16
	v_mov_b32_e32 v20, v0
	v_mov_b32_e32 v21, v4
	v_mov_b32_e32 v4, v1
	ds_read2_b32 v[0:1], v27 offset0:32 offset1:48
	ds_read2_b32 v[32:33], v32 offset0:32 offset1:48
	s_waitcnt lgkmcnt(3)
	v_pk_add_f32 v[20:21], v[20:21], v[18:19]
	s_waitcnt lgkmcnt(2)
	v_pk_add_f32 v[18:19], v[4:5], v[28:29]
	v_mov_b32_e32 v4, v8
	v_mov_b32_e32 v5, v12
	v_mov_b32_e32 v12, v9
	s_waitcnt lgkmcnt(1)
	v_pk_add_f32 v[4:5], v[4:5], v[0:1]
	s_waitcnt lgkmcnt(0)
	v_pk_add_f32 v[0:1], v[12:13], v[32:33]
	v_and_b32_e32 v13, 64, v223
	v_xor_b32_e32 v12, 1, v223
	v_add_u32_e32 v27, 64, v13
	v_cmp_lt_i32_e32 vcc, v12, v27
	v_pk_mul_f32 v[30:31], v[20:21], v[20:21]
	v_pk_mul_f32 v[28:29], v[18:19], v[18:19]
	v_cndmask_b32_e32 v12, v223, v12, vcc
	v_pk_mul_f32 v[34:35], v[4:5], v[4:5]
	v_pk_mul_f32 v[8:9], v[0:1], v[0:1]
	v_lshlrev_b32_e32 v45, 2, v12
	v_mov_b32_e32 v12, v28
	v_mov_b32_e32 v13, v30
	v_mov_b32_e32 v30, v29
	v_pk_add_f32 v[12:13], v[12:13], v[30:31]
	v_mov_b32_e32 v28, v8
	v_mov_b32_e32 v29, v34
	v_pk_add_f32 v[12:13], v[12:13], v[28:29]
	v_mov_b32_e32 v34, v9
	v_pk_add_f32 v[8:9], v[12:13], v[34:35]
	ds_bpermute_b32 v13, v45, v9
	ds_bpermute_b32 v12, v45, v8
	v_xor_b32_e32 v28, 2, v223
	v_cmp_lt_i32_e32 vcc, v28, v27
	s_mov_b32 s8, 0x358637bd
	s_mov_b32 s10, 0x3c800000
	v_cndmask_b32_e32 v28, v223, v28, vcc
	v_lshlrev_b32_e32 v56, 2, v28
	s_waitcnt lgkmcnt(0)
	v_pk_add_f32 v[8:9], v[8:9], v[12:13]
	ds_bpermute_b32 v13, v56, v9
	ds_bpermute_b32 v12, v56, v8
	v_xor_b32_e32 v28, 4, v223
	v_cmp_lt_i32_e32 vcc, v28, v27
	s_mov_b32 s1, 0x800000
	v_or_b32_e32 v48, 2, v39
	v_cndmask_b32_e32 v28, v223, v28, vcc
	v_lshlrev_b32_e32 v57, 2, v28
	s_waitcnt lgkmcnt(0)
	v_pk_add_f32 v[8:9], v[8:9], v[12:13]
	ds_bpermute_b32 v13, v57, v9
	ds_bpermute_b32 v12, v57, v8
	v_xor_b32_e32 v28, 8, v223
	v_cmp_lt_i32_e32 vcc, v28, v27
	v_or_b32_e32 v39, 3, v39
	s_mov_b32 s72, 0x800000
	v_cndmask_b32_e32 v27, v223, v28, vcc
	v_lshlrev_b32_e32 v58, 2, v27
	s_waitcnt lgkmcnt(0)
	v_pk_add_f32 v[8:9], v[8:9], v[12:13]
	ds_bpermute_b32 v13, v58, v9
	ds_bpermute_b32 v12, v58, v8
	v_ashrrev_i32_e32 v27, 31, v26
	v_lshlrev_b64 v[26:27], 11, v[26:27]
	s_mov_b32 s96, s0
	s_waitcnt lgkmcnt(0)
	v_pk_add_f32 v[8:9], v[8:9], v[12:13]
	v_mov_b64_e32 v[12:13], s[8:9]
	v_pk_fma_f32 v[30:31], v[8:9], s[10:11], v[12:13] op_sel_hi:[1,0,0]
	s_add_u32 s8, s60, s66
	v_mul_f32_e32 v8, 0x4b800000, v31
	v_cmp_gt_f32_e32 vcc, s1, v31
	s_addc_u32 s9, s61, 0
	s_waitcnt vmcnt(1)
	v_lshlrev_b32_e32 v28, 16, v37
	v_cndmask_b32_e32 v8, v31, v8, vcc
	v_rsq_f32_e32 v8, v8
	s_add_i32 s93, s93, s0
	s_cmpk_gt_i32 s93, 0xfff
	v_mul_f32_e32 v9, 0x45800000, v8
	v_cndmask_b32_e32 v31, v8, v9, vcc
	v_mul_f32_e32 v8, 0xbfb8aa3b, v28
	v_exp_f32_e32 v29, v8
	v_lshl_add_u64 v[8:9], s[8:9], 0, v[24:25]
	v_mul_f32_e32 v32, v20, v31
	s_waitcnt vmcnt(0)
	v_mul_f32_e32 v32, v32, v42
	v_add_f32_e32 v29, 1.0, v29
	v_div_scale_f32 v33, s[8:9], v29, v29, v28
	v_rcp_f32_e32 v34, v33
	global_load_dword v41, v40, s[2:3] offset:64
	global_load_dword v37, v40, s[2:3] offset:128
	global_load_dword v20, v40, s[2:3] offset:192
	v_mul_f32_e32 v4, v4, v31
	v_fma_f32 v35, -v33, v34, 1.0
	v_fmac_f32_e32 v34, v35, v34
	v_div_scale_f32 v35, vcc, v28, v29, v28
	v_mul_f32_e32 v44, v35, v34
	v_fma_f32 v46, -v33, v44, v35
	v_fmac_f32_e32 v44, v46, v34
	v_fma_f32 v33, -v33, v44, v35
	v_div_fmas_f32 v33, v33, v34, v44
	v_div_fixup_f32 v28, v33, v29, v28
	v_mul_f32_e32 v28, v32, v28
	v_lshl_add_u64 v[32:33], v[8:9], 0, v[26:27]
	v_or_b32_e32 v26, v38, v43
	v_cvt_pk_bf16_f32 v28, v28, s0
	v_sub_u32_e32 v26, s6, v26
	global_store_short v[32:33], v28, off
	v_mad_i64_i32 v[28:29], s[2:3], v26, s71, v[22:23]
	v_lshl_add_u64 v[28:29], v[28:29], 0, s[66:67]
	v_lshl_add_u64 v[34:35], v[28:29], 0, v[24:25]
	global_load_ushort v43, v[34:35], off offset:1024
	v_mul_f32_e32 v46, 0x4b800000, v30
	v_cmp_gt_f32_e32 vcc, s1, v30
	v_or_b32_e32 v27, v38, v48
	v_sub_u32_e32 v44, s6, v27
	v_cndmask_b32_e32 v30, v30, v46, vcc
	v_rsq_f32_e32 v30, v30
	v_ashrrev_i32_e32 v27, 31, v26
	v_mad_i64_i32 v[28:29], s[2:3], v44, s71, v[22:23]
	v_mul_f32_e32 v47, 0x45800000, v30
	v_cndmask_b32_e32 v30, v30, v47, vcc
	v_mul_f32_e32 v18, v18, v30
	v_mul_f32_e32 v18, v42, v18
	v_lshlrev_b64 v[26:27], 11, v[26:27]
	v_lshl_add_u64 v[28:29], v[28:29], 0, s[66:67]
	v_lshl_add_u64 v[26:27], v[8:9], 0, v[26:27]
	v_lshl_add_u64 v[28:29], v[28:29], 0, v[24:25]
	v_mul_f32_e32 v0, v0, v30
	v_mul_f32_e32 v1, v1, v30
	s_waitcnt vmcnt(3)
	v_mul_f32_e32 v4, v4, v37
	v_mul_f32_e32 v0, v0, v37
	s_waitcnt vmcnt(2)
	v_mul_f32_e32 v1, v1, v20
	s_waitcnt vmcnt(0)
; __device__ __forceinline__ float bf2f(u16 h) { return __uint_as_float(((unsigned)h) << 16); }
; __device__ __forceinline__ float silu_f(float x) { return x / (1.f + __expf(-x)); }
; __device__ __forceinline__ void gla_out_job(const Params& p, int layer, int half, int job, char* smem) {
;     ...
; #pragma unroll
;     for (int nt = 0; nt < 4; ++nt) {
;       int v = nt * 16 + fr;
;       float gw = gn[v];
; #pragma unroll
;       for (int j = 0; j < 4; ++j) {
;         int prow = 63 - (wid * 16 + fq * 4 + j);
;         size_t tok = (size_t)(tok0 + prow);
;         float g = bf2f(proj[tok * PW + 512 + hd * 64 + v]);
;         y[tok * DM + hd * 64 + v] = f2bf(tot[nt][j] * ss[j] * gw * silu_f(g));
;       }
	v_lshlrev_b32_e32 v43, 16, v43
	v_mul_f32_e32 v46, 0xbfb8aa3b, v43
	v_exp_f32_e32 v46, v46
	s_nop 0
	v_add_f32_e32 v46, 1.0, v46
	v_div_scale_f32 v47, s[2:3], v46, v46, v43
	v_rcp_f32_e32 v49, v47
	v_div_scale_f32 v50, vcc, v43, v46, v43
	v_fma_f32 v51, -v47, v49, 1.0
	v_fmac_f32_e32 v49, v51, v49
	v_mul_f32_e32 v51, v50, v49
	v_fma_f32 v52, -v47, v51, v50
	v_fmac_f32_e32 v51, v52, v49
	v_fma_f32 v47, -v47, v51, v50
	v_div_fmas_f32 v47, v47, v49, v51
	v_div_fixup_f32 v43, v47, v46, v43
	v_mul_f32_e32 v18, v18, v43
	v_cvt_pk_bf16_f32 v18, v18, s0
	global_store_short v[26:27], v18, off
	global_load_ushort v18, v[28:29], off offset:1024
	v_mov_b32_e32 v46, v2
	v_mov_b32_e32 v2, v10
	v_sub_u32_e32 v10, v36, v48
	v_mov_b32_e32 v47, v6
	v_mov_b32_e32 v6, v3
	v_mov_b32_e32 v3, v14
	v_sub_u32_e32 v14, v36, v39
	v_lshlrev_b32_e32 v10, 8, v10
	v_lshlrev_b32_e32 v14, 8, v14
	v_add3_u32 v10, s65, v10, v40
	v_add3_u32 v14, s65, v14, v40
	v_add_u32_e32 v10, 0xf800, v10
	v_add_u32_e32 v14, 0xf800, v14
	ds_read2_b32 v[48:49], v10 offset1:16
	ds_read2_b32 v[50:51], v14 offset1:16
	ds_read2_b32 v[52:53], v10 offset0:32 offset1:48
	ds_read2_b32 v[54:55], v14 offset0:32 offset1:48
	v_mov_b32_e32 v14, v11
	s_waitcnt lgkmcnt(3)
	v_pk_add_f32 v[46:47], v[46:47], v[48:49]
	s_waitcnt lgkmcnt(2)
	v_pk_add_f32 v[48:49], v[6:7], v[50:51]
	s_waitcnt lgkmcnt(1)
	v_pk_add_f32 v[10:11], v[2:3], v[52:53]
	s_waitcnt lgkmcnt(0)
	v_pk_add_f32 v[2:3], v[14:15], v[54:55]
	v_pk_mul_f32 v[6:7], v[46:47], v[46:47]
	v_pk_mul_f32 v[14:15], v[48:49], v[48:49]
	v_pk_mul_f32 v[50:51], v[10:11], v[10:11]
	v_pk_mul_f32 v[52:53], v[2:3], v[2:3]
	v_mov_b32_e32 v54, v14
	v_mov_b32_e32 v55, v6
	v_mov_b32_e32 v6, v15
	v_mov_b32_e32 v14, v52
	v_mov_b32_e32 v15, v50
	v_pk_add_f32 v[6:7], v[54:55], v[6:7]
	v_mov_b32_e32 v50, v53
	v_pk_add_f32 v[6:7], v[6:7], v[14:15]
	v_or_b32_e32 v36, v38, v39
	v_pk_add_f32 v[6:7], v[6:7], v[50:51]
	ds_bpermute_b32 v15, v45, v7
	ds_bpermute_b32 v14, v45, v6
	v_sub_u32_e32 v38, s6, v36
	v_mad_i64_i32 v[22:23], s[2:3], v38, s71, v[22:23]
	v_lshl_add_u64 v[22:23], v[22:23], 0, s[66:67]
	s_waitcnt lgkmcnt(0)
	v_pk_add_f32 v[6:7], v[6:7], v[14:15]
	ds_bpermute_b32 v15, v56, v7
	ds_bpermute_b32 v14, v56, v6
	v_lshl_add_u64 v[22:23], v[22:23], 0, v[24:25]
	v_ashrrev_i32_e32 v45, 31, v44
	v_readlane_b32 s66, v254, 4
	s_waitcnt lgkmcnt(0)
	v_pk_add_f32 v[6:7], v[6:7], v[14:15]
	ds_bpermute_b32 v15, v57, v7
	ds_bpermute_b32 v14, v57, v6
	s_waitcnt lgkmcnt(0)
	v_pk_add_f32 v[6:7], v[6:7], v[14:15]
	ds_bpermute_b32 v51, v58, v7
	ds_bpermute_b32 v50, v58, v6
	v_lshlrev_b64 v[14:15], 11, v[44:45]
	v_lshl_add_u64 v[14:15], v[8:9], 0, v[14:15]
	s_waitcnt lgkmcnt(0)
	v_pk_add_f32 v[6:7], v[6:7], v[50:51]
	s_nop 0
	v_pk_fma_f32 v[12:13], v[6:7], s[10:11], v[12:13] op_sel_hi:[1,0,0]
	s_waitcnt vmcnt(0)
	v_lshlrev_b32_e32 v7, 16, v18
	v_mul_f32_e32 v6, 0x4b800000, v13
	v_cmp_gt_f32_e32 vcc, s1, v13
	s_nop 1
	v_cndmask_b32_e32 v6, v13, v6, vcc
	v_mul_f32_e32 v13, 0xbfb8aa3b, v7
	v_exp_f32_e32 v13, v13
	v_rsq_f32_e32 v6, v6
	v_add_f32_e32 v13, 1.0, v13
	v_div_scale_f32 v24, s[2:3], v13, v13, v7
	v_rcp_f32_e32 v25, v24
	v_mul_f32_e32 v18, 0x45800000, v6
	v_cndmask_b32_e32 v18, v6, v18, vcc
	v_div_scale_f32 v36, vcc, v7, v13, v7
	v_fma_f32 v39, -v24, v25, 1.0
	v_fmac_f32_e32 v25, v39, v25
	v_mul_f32_e32 v39, v36, v25
	v_fma_f32 v40, -v24, v39, v36
	v_fmac_f32_e32 v39, v40, v25
	v_fma_f32 v24, -v24, v39, v36
	v_mul_f32_e32 v6, v46, v18
	v_div_fmas_f32 v24, v24, v25, v39
	v_mul_f32_e32 v6, v42, v6
	v_div_fixup_f32 v7, v24, v13, v7
	v_mul_f32_e32 v6, v6, v7
	v_cvt_pk_bf16_f32 v6, v6, s0
	global_store_short v[14:15], v6, off
	global_load_ushort v13, v[22:23], off offset:1024
	global_load_ushort v202, v[16:17], off offset:1056
	global_load_ushort v203, v[34:35], off offset:1056
	global_load_ushort v204, v[28:29], off offset:1056
	global_load_ushort v205, v[22:23], off offset:1056
	global_load_ushort v206, v[16:17], off offset:1088
	global_load_ushort v207, v[34:35], off offset:1088
	global_load_ushort v208, v[28:29], off offset:1088
	global_load_ushort v209, v[22:23], off offset:1088
	global_load_ushort v210, v[16:17], off offset:1120
	global_load_ushort v211, v[34:35], off offset:1120
	global_load_ushort v212, v[28:29], off offset:1120
	global_load_ushort v213, v[22:23], off offset:1120
	v_ashrrev_i32_e32 v39, 31, v38
	v_lshlrev_b64 v[6:7], 11, v[38:39]
	v_lshl_add_u64 v[6:7], v[8:9], 0, v[6:7]
	v_mul_f32_e32 v8, 0x4b800000, v12
	v_cmp_gt_f32_e32 vcc, s1, v12
	s_waitcnt vmcnt(12)
	v_lshlrev_b32_e32 v9, 16, v13
	v_cndmask_b32_e32 v8, v12, v8, vcc
	v_mul_f32_e32 v12, 0xbfb8aa3b, v9
	v_exp_f32_e32 v12, v12
	v_rsq_f32_e32 v8, v8
	v_add_f32_e32 v12, 1.0, v12
	v_div_scale_f32 v24, s[2:3], v12, v12, v9
	v_rcp_f32_e32 v25, v24
	v_mul_f32_e32 v13, 0x45800000, v8
	v_cndmask_b32_e32 v8, v8, v13, vcc
	v_div_scale_f32 v36, vcc, v9, v12, v9
	v_fma_f32 v38, -v24, v25, 1.0
	v_fmac_f32_e32 v25, v38, v25
	v_mul_f32_e32 v38, v36, v25
	v_fma_f32 v39, -v24, v38, v36
	v_fmac_f32_e32 v38, v39, v25
	v_fma_f32 v24, -v24, v38, v36
	v_mul_f32_e32 v13, v48, v8
	v_div_fmas_f32 v24, v24, v25, v38
	v_mul_f32_e32 v13, v42, v13
	v_div_fixup_f32 v9, v24, v12, v9
	v_mul_f32_e32 v9, v13, v9
	v_cvt_pk_bf16_f32 v9, v9, s0
	global_store_short v[6:7], v9, off
	s_nop 0
	v_mul_f32_e32 v13, v21, v31
	v_mul_f32_e32 v13, v13, v41
	v_mul_f32_e32 v2, v2, v8
	v_mul_f32_e32 v2, v2, v37
	s_waitcnt vmcnt(12)
; __device__ __forceinline__ float bf2f(u16 h) { return __uint_as_float(((unsigned)h) << 16); }
; __device__ __forceinline__ float silu_f(float x) { return x / (1.f + __expf(-x)); }
; __device__ __forceinline__ void gla_out_job(const Params& p, int layer, int half, int job, char* smem) {
;     ...
; #pragma unroll
;       for (int j = 0; j < 4; ++j) {
;         int prow = 63 - (wid * 16 + fq * 4 + j);
;         size_t tok = (size_t)(tok0 + prow);
;         float g = bf2f(proj[tok * PW + 512 + hd * 64 + v]);
;         y[tok * DM + hd * 64 + v] = f2bf(tot[nt][j] * ss[j] * gw * silu_f(g));
;       }
	v_mov_b32_e32 v9, v202
	v_lshlrev_b32_e32 v9, 16, v9
	v_mul_f32_e32 v12, 0xbfb8aa3b, v9
	v_exp_f32_e32 v12, v12
	s_nop 0
	v_add_f32_e32 v12, 1.0, v12
	v_div_scale_f32 v21, s[2:3], v12, v12, v9
	v_rcp_f32_e32 v24, v21
	v_div_scale_f32 v25, vcc, v9, v12, v9
	v_fma_f32 v36, -v21, v24, 1.0
	v_fmac_f32_e32 v24, v36, v24
	v_mul_f32_e32 v36, v25, v24
	v_fma_f32 v38, -v21, v36, v25
	v_fmac_f32_e32 v36, v38, v24
	v_fma_f32 v21, -v21, v36, v25
	v_div_fmas_f32 v21, v21, v24, v36
	v_div_fixup_f32 v9, v21, v12, v9
	v_mul_f32_e32 v9, v13, v9
	v_cvt_pk_bf16_f32 v9, v9, s0
	global_store_short v[32:33], v9, off offset:32
	s_nop 0
	v_mul_f32_e32 v13, v19, v30
	v_mul_f32_e32 v13, v13, v41
	s_waitcnt vmcnt(12)
	v_mov_b32_e32 v9, v203
	v_lshlrev_b32_e32 v9, 16, v9
	v_mul_f32_e32 v12, 0xbfb8aa3b, v9
	v_exp_f32_e32 v12, v12
	s_nop 0
	v_add_f32_e32 v12, 1.0, v12
	v_div_scale_f32 v19, s[2:3], v12, v12, v9
	v_rcp_f32_e32 v21, v19
	v_div_scale_f32 v24, vcc, v9, v12, v9
	v_fma_f32 v25, -v19, v21, 1.0
	v_fmac_f32_e32 v21, v25, v21
	v_mul_f32_e32 v25, v24, v21
	v_fma_f32 v36, -v19, v25, v24
	v_fmac_f32_e32 v25, v36, v21
	v_fma_f32 v19, -v19, v25, v24
	v_div_fmas_f32 v19, v19, v21, v25
	v_div_fixup_f32 v9, v19, v12, v9
	v_mul_f32_e32 v9, v13, v9
	v_cvt_pk_bf16_f32 v9, v9, s0
	global_store_short v[26:27], v9, off offset:32
	s_nop 0
	v_mul_f32_e32 v13, v47, v18
	v_mul_f32_e32 v13, v13, v41
	s_waitcnt vmcnt(12)
	v_mov_b32_e32 v9, v204
	v_lshlrev_b32_e32 v9, 16, v9
	v_mul_f32_e32 v12, 0xbfb8aa3b, v9
	v_exp_f32_e32 v12, v12
	s_nop 0
	v_add_f32_e32 v12, 1.0, v12
	v_div_scale_f32 v19, s[2:3], v12, v12, v9
	v_rcp_f32_e32 v21, v19
	v_div_scale_f32 v24, vcc, v9, v12, v9
	v_fma_f32 v25, -v19, v21, 1.0
	v_fmac_f32_e32 v21, v25, v21
	v_mul_f32_e32 v25, v24, v21
	v_fma_f32 v36, -v19, v25, v24
	v_fmac_f32_e32 v25, v36, v21
	v_fma_f32 v19, -v19, v25, v24
	v_div_fmas_f32 v19, v19, v21, v25
	v_div_fixup_f32 v9, v19, v12, v9
	v_mul_f32_e32 v9, v13, v9
	v_cvt_pk_bf16_f32 v9, v9, s0
	global_store_short v[14:15], v9, off offset:32
	s_nop 0
	v_mul_f32_e32 v13, v49, v8
	v_mul_f32_e32 v13, v41, v13
	s_waitcnt vmcnt(12)
	v_mov_b32_e32 v9, v205
	v_lshlrev_b32_e32 v9, 16, v9
	v_mul_f32_e32 v12, 0xbfb8aa3b, v9
	v_exp_f32_e32 v12, v12
	s_nop 0
	v_add_f32_e32 v12, 1.0, v12
	v_div_scale_f32 v19, s[2:3], v12, v12, v9
	v_rcp_f32_e32 v21, v19
	v_div_scale_f32 v24, vcc, v9, v12, v9
	v_fma_f32 v25, -v19, v21, 1.0
	v_fmac_f32_e32 v21, v25, v21
	v_mul_f32_e32 v25, v24, v21
	v_fma_f32 v36, -v19, v25, v24
	v_fmac_f32_e32 v25, v36, v21
	v_fma_f32 v19, -v19, v25, v24
	v_div_fmas_f32 v19, v19, v21, v25
	v_div_fixup_f32 v9, v19, v12, v9
	v_mul_f32_e32 v9, v13, v9
	v_cvt_pk_bf16_f32 v9, v9, s0
	global_store_short v[6:7], v9, off offset:32
	s_nop 0
	s_waitcnt vmcnt(12)
	v_mov_b32_e32 v9, v206
	v_lshlrev_b32_e32 v9, 16, v9
	v_mul_f32_e32 v12, 0xbfb8aa3b, v9
	v_exp_f32_e32 v12, v12
	s_nop 0
	v_add_f32_e32 v12, 1.0, v12
	v_div_scale_f32 v13, s[2:3], v12, v12, v9
	v_rcp_f32_e32 v19, v13
	v_div_scale_f32 v21, vcc, v9, v12, v9
	v_fma_f32 v24, -v13, v19, 1.0
	v_fmac_f32_e32 v19, v24, v19
	v_mul_f32_e32 v24, v21, v19
	v_fma_f32 v25, -v13, v24, v21
	v_fmac_f32_e32 v24, v25, v19
	v_fma_f32 v13, -v13, v24, v21
	v_div_fmas_f32 v13, v13, v19, v24
	v_div_fixup_f32 v9, v13, v12, v9
	v_mul_f32_e32 v4, v4, v9
	v_cvt_pk_bf16_f32 v4, v4, s0
	global_store_short v[32:33], v4, off offset:64
	s_nop 0
	s_waitcnt vmcnt(12)
	v_mov_b32_e32 v4, v207
	v_lshlrev_b32_e32 v4, 16, v4
	v_mul_f32_e32 v9, 0xbfb8aa3b, v4
	v_exp_f32_e32 v9, v9
	s_nop 0
	v_add_f32_e32 v9, 1.0, v9
	v_div_scale_f32 v12, s[2:3], v9, v9, v4
	v_rcp_f32_e32 v13, v12
	v_div_scale_f32 v19, vcc, v4, v9, v4
	v_fma_f32 v21, -v12, v13, 1.0
	v_fmac_f32_e32 v13, v21, v13
	v_mul_f32_e32 v21, v19, v13
	v_fma_f32 v24, -v12, v21, v19
	v_fmac_f32_e32 v21, v24, v13
	v_fma_f32 v12, -v12, v21, v19
	v_div_fmas_f32 v12, v12, v13, v21
	v_div_fixup_f32 v4, v12, v9, v4
	v_mul_f32_e32 v0, v0, v4
	v_cvt_pk_bf16_f32 v0, v0, s0
	global_store_short v[26:27], v0, off offset:64
	s_nop 0
	v_mul_f32_e32 v9, v10, v18
	v_mul_f32_e32 v9, v9, v37
	s_waitcnt vmcnt(12)
; __device__ __forceinline__ float bf2f(u16 h) { return __uint_as_float(((unsigned)h) << 16); }
; __device__ __forceinline__ float silu_f(float x) { return x / (1.f + __expf(-x)); }
; __device__ __forceinline__ void gla_out_job(const Params& p, int layer, int half, int job, char* smem) {
;     ...
; #pragma unroll
;       for (int j = 0; j < 4; ++j) {
;         int prow = 63 - (wid * 16 + fq * 4 + j);
;         size_t tok = (size_t)(tok0 + prow);
;         float g = bf2f(proj[tok * PW + 512 + hd * 64 + v]);
;         y[tok * DM + hd * 64 + v] = f2bf(tot[nt][j] * ss[j] * gw * silu_f(g));
;       }
;     }
;   }
;   __syncthreads();
	v_mov_b32_e32 v0, v208
	v_lshlrev_b32_e32 v0, 16, v0
	v_mul_f32_e32 v4, 0xbfb8aa3b, v0
	v_exp_f32_e32 v4, v4
	s_nop 0
	v_add_f32_e32 v4, 1.0, v4
	v_div_scale_f32 v10, s[2:3], v4, v4, v0
	v_rcp_f32_e32 v12, v10
	v_div_scale_f32 v13, vcc, v0, v4, v0
	v_fma_f32 v19, -v10, v12, 1.0
	v_fmac_f32_e32 v12, v19, v12
	v_mul_f32_e32 v19, v13, v12
	v_fma_f32 v21, -v10, v19, v13
	v_fmac_f32_e32 v19, v21, v12
	v_fma_f32 v10, -v10, v19, v13
	v_div_fmas_f32 v10, v10, v12, v19
	v_div_fixup_f32 v0, v10, v4, v0
	v_mul_f32_e32 v0, v9, v0
	v_cvt_pk_bf16_f32 v0, v0, s0
	global_store_short v[14:15], v0, off offset:64
	s_nop 0
	s_waitcnt vmcnt(12)
	v_mov_b32_e32 v0, v209
	v_lshlrev_b32_e32 v0, 16, v0
	v_mul_f32_e32 v4, 0xbfb8aa3b, v0
	v_exp_f32_e32 v4, v4
	s_nop 0
	v_add_f32_e32 v4, 1.0, v4
	v_div_scale_f32 v9, s[2:3], v4, v4, v0
	v_rcp_f32_e32 v10, v9
	v_div_scale_f32 v12, vcc, v0, v4, v0
	v_fma_f32 v13, -v9, v10, 1.0
	v_fmac_f32_e32 v10, v13, v10
	v_mul_f32_e32 v13, v12, v10
	v_fma_f32 v19, -v9, v13, v12
	v_fmac_f32_e32 v13, v19, v10
	v_fma_f32 v9, -v9, v13, v12
	v_div_fmas_f32 v9, v9, v10, v13
	v_div_fixup_f32 v0, v9, v4, v0
	v_mul_f32_e32 v0, v2, v0
	v_cvt_pk_bf16_f32 v0, v0, s0
	global_store_short v[6:7], v0, off offset:64
	s_nop 0
	v_mul_f32_e32 v4, v5, v31
	v_mul_f32_e32 v4, v4, v20
	s_waitcnt vmcnt(12)
	v_mov_b32_e32 v0, v210
	v_lshlrev_b32_e32 v0, 16, v0
	v_mul_f32_e32 v2, 0xbfb8aa3b, v0
	v_exp_f32_e32 v2, v2
	s_nop 0
	v_add_f32_e32 v2, 1.0, v2
	v_div_scale_f32 v5, s[2:3], v2, v2, v0
	v_rcp_f32_e32 v9, v5
	v_div_scale_f32 v10, vcc, v0, v2, v0
	v_fma_f32 v12, -v5, v9, 1.0
	v_fmac_f32_e32 v9, v12, v9
	v_mul_f32_e32 v12, v10, v9
	v_fma_f32 v13, -v5, v12, v10
	v_fmac_f32_e32 v12, v13, v9
	v_fma_f32 v5, -v5, v12, v10
	v_div_fmas_f32 v5, v5, v9, v12
	v_div_fixup_f32 v0, v5, v2, v0
	v_mul_f32_e32 v0, v4, v0
	v_cvt_pk_bf16_f32 v0, v0, s0
	global_store_short v[32:33], v0, off offset:96
	s_nop 0
	s_waitcnt vmcnt(12)
	v_mov_b32_e32 v0, v211
	v_lshlrev_b32_e32 v0, 16, v0
	v_mul_f32_e32 v2, 0xbfb8aa3b, v0
	v_exp_f32_e32 v2, v2
	s_nop 0
	v_add_f32_e32 v2, 1.0, v2
	v_div_scale_f32 v4, s[2:3], v2, v2, v0
	v_rcp_f32_e32 v5, v4
	v_div_scale_f32 v9, vcc, v0, v2, v0
	v_fma_f32 v10, -v4, v5, 1.0
	v_fmac_f32_e32 v5, v10, v5
	v_mul_f32_e32 v10, v9, v5
	v_fma_f32 v12, -v4, v10, v9
	v_fmac_f32_e32 v10, v12, v5
	v_fma_f32 v4, -v4, v10, v9
	v_div_fmas_f32 v4, v4, v5, v10
	v_div_fixup_f32 v0, v4, v2, v0
	v_mul_f32_e32 v0, v1, v0
	v_cvt_pk_bf16_f32 v0, v0, s0
	global_store_short v[26:27], v0, off offset:96
	s_nop 0
	v_mul_f32_e32 v2, v11, v18
	v_mul_f32_e32 v2, v2, v20
	s_waitcnt vmcnt(12)
	v_mov_b32_e32 v0, v212
	v_lshlrev_b32_e32 v0, 16, v0
	v_mul_f32_e32 v1, 0xbfb8aa3b, v0
	v_exp_f32_e32 v1, v1
	s_nop 0
	v_add_f32_e32 v1, 1.0, v1
	v_div_scale_f32 v4, s[2:3], v1, v1, v0
	v_rcp_f32_e32 v5, v4
	v_div_scale_f32 v9, vcc, v0, v1, v0
	v_fma_f32 v10, -v4, v5, 1.0
	v_fmac_f32_e32 v5, v10, v5
	v_mul_f32_e32 v10, v9, v5
	v_fma_f32 v11, -v4, v10, v9
	v_fmac_f32_e32 v10, v11, v5
	v_fma_f32 v4, -v4, v10, v9
	v_div_fmas_f32 v4, v4, v5, v10
	v_div_fixup_f32 v0, v4, v1, v0
	v_mul_f32_e32 v0, v2, v0
	v_cvt_pk_bf16_f32 v0, v0, s0
	global_store_short v[14:15], v0, off offset:96
	s_nop 0
	v_mul_f32_e32 v2, v3, v8
	v_mul_f32_e32 v2, v2, v20
	s_waitcnt vmcnt(12)
	v_mov_b32_e32 v0, v213
	v_lshlrev_b32_e32 v0, 16, v0
	v_mul_f32_e32 v1, 0xbfb8aa3b, v0
	v_exp_f32_e32 v1, v1
	s_nop 0
	v_add_f32_e32 v1, 1.0, v1
	v_div_scale_f32 v3, s[2:3], v1, v1, v0
	v_rcp_f32_e32 v4, v3
	v_div_scale_f32 v5, vcc, v0, v1, v0
	v_fma_f32 v8, -v3, v4, 1.0
	v_fmac_f32_e32 v4, v8, v4
	v_mul_f32_e32 v8, v5, v4
	v_fma_f32 v9, -v3, v8, v5
	v_fmac_f32_e32 v8, v9, v4
	v_fma_f32 v3, -v3, v8, v5
	v_div_fmas_f32 v3, v3, v4, v8
	v_div_fixup_f32 v0, v3, v1, v0
	v_mul_f32_e32 v0, v2, v0
	v_cvt_pk_bf16_f32 v0, v0, s0
	global_store_short v[6:7], v0, off offset:96
	s_barrier
	s_cbranch_scc1 .LBB0_232

; __device__ __forceinline__ int get_tid() { int t = threadIdx.x & 255; asm volatile("" : "+v"(t)); return t; }
; __device__ __forceinline__ void phase_gla_scan(const Params& p, int half, int bid, int nb) {
;     ...
;   for (int job = bid; job < total; job += nb) {
;     int chain = job >> 3;
;     int e = (job & 7) * 256 + get_tid();
;     size_t base = (size_t)chain * N;
;     float st = 0.f;
;     for (int n0 = 0; n0 < N; n0 += 8) {
;       float kv[8], dc[8];
; #pragma unroll
;       for (int u = 0; u < 8; ++u) {
;         kv[u] = __builtin_nontemporal_load(gkv + (base + n0 + u) * 2048 + e);
;         dc[u] = gdec[(base + n0 + u) * 32 + (e & 31)];
;       }
; #pragma unroll
;       for (int u = 0; u < 8; ++u) {
;         __builtin_nontemporal_store(st, gprev + (base + n0 + u) * 2048 + e);
;         st = dc[u] * st + kv[u];
;       }
;     }
.LBB0_236:
	s_waitcnt lgkmcnt(0)
	s_add_u32 s10, s2, 0x19800000
	s_addc_u32 s11, s3, 0
	s_add_u32 s12, s2, 0x1d800000
	s_addc_u32 s13, s3, 0
	s_add_u32 s0, s2, 0x21800000
	s_addc_u32 s1, s3, 0
	s_ashr_i32 s14, s9, 3
	s_lshl_b32 s14, s14, s7
	v_mov_b32_e32 v2, v197
	v_and_b32_e32 v0, 31, v2
	s_and_b32 vcc_lo, s8, 0x700
	v_add_u32_e32 v2, vcc_lo, v2
	v_lshlrev_b32_e32 v2, 2, v2
	s_lshl_b32 vcc_lo, s14, 13
	v_add_u32_e32 v48, vcc_lo, v2
	v_lshlrev_b32_e32 v0, 2, v0
	s_lshl_b32 vcc_lo, s14, 7
	v_add_u32_e32 v0, vcc_lo, v0
	v_add_u32_e32 v49, 0x2000, v48
	v_add_u32_e32 v50, 0x4000, v48
	v_add_u32_e32 v51, 0x6000, v48
	v_mov_b32_e32 v52, v48
	v_mov_b32_e32 v53, v49
	v_mov_b32_e32 v54, v50
	v_mov_b32_e32 v55, v51
	v_mov_b32_e32 v4, 0
	s_lshr_b32 s14, s92, 4
	s_add_i32 s14, s14, -2
	global_load_dword v16, v48, s[10:11] nt
	global_load_dword v17, v49, s[10:11] nt
	global_load_dword v18, v50, s[10:11] nt
	global_load_dword v19, v51, s[10:11] nt
	global_load_dword v20, v0, s[0:1]
	global_load_dword v21, v0, s[0:1] offset:128
	global_load_dword v22, v0, s[0:1] offset:256
	global_load_dword v23, v0, s[0:1] offset:384
	v_add_u32_e32 v48, 0x8000, v48
	v_add_u32_e32 v49, 0x8000, v49
	v_add_u32_e32 v50, 0x8000, v50
	v_add_u32_e32 v51, 0x8000, v51
	v_add_u32_e32 v0, 0x200, v0
	global_load_dword v24, v48, s[10:11] nt
	global_load_dword v25, v49, s[10:11] nt
	global_load_dword v26, v50, s[10:11] nt
	global_load_dword v27, v51, s[10:11] nt
	global_load_dword v28, v0, s[0:1]
	global_load_dword v29, v0, s[0:1] offset:128
	global_load_dword v30, v0, s[0:1] offset:256
	global_load_dword v31, v0, s[0:1] offset:384
	v_add_u32_e32 v48, 0x8000, v48
	v_add_u32_e32 v49, 0x8000, v49
	v_add_u32_e32 v50, 0x8000, v50
	v_add_u32_e32 v51, 0x8000, v51
	v_add_u32_e32 v0, 0x200, v0
	global_load_dword v32, v48, s[10:11] nt
	global_load_dword v33, v49, s[10:11] nt
	global_load_dword v34, v50, s[10:11] nt
	global_load_dword v35, v51, s[10:11] nt
	global_load_dword v36, v0, s[0:1]
	global_load_dword v37, v0, s[0:1] offset:128
	global_load_dword v38, v0, s[0:1] offset:256
	global_load_dword v39, v0, s[0:1] offset:384
	v_add_u32_e32 v48, 0x8000, v48
	v_add_u32_e32 v49, 0x8000, v49
	v_add_u32_e32 v50, 0x8000, v50
	v_add_u32_e32 v51, 0x8000, v51
	v_add_u32_e32 v0, 0x200, v0
	global_load_dword v40, v48, s[10:11] nt
	global_load_dword v41, v49, s[10:11] nt
	global_load_dword v42, v50, s[10:11] nt
	global_load_dword v43, v51, s[10:11] nt
	global_load_dword v44, v0, s[0:1]
	global_load_dword v45, v0, s[0:1] offset:128
	global_load_dword v46, v0, s[0:1] offset:256
	global_load_dword v47, v0, s[0:1] offset:384
	v_add_u32_e32 v48, 0x8000, v48
	v_add_u32_e32 v49, 0x8000, v49
	v_add_u32_e32 v50, 0x8000, v50
	v_add_u32_e32 v51, 0x8000, v51
	v_add_u32_e32 v0, 0x200, v0
	s_waitcnt vmcnt(24)
	global_store_dword v52, v4, s[12:13] nt
	v_fmac_f32_e32 v16, v4, v20
	global_store_dword v53, v16, s[12:13] nt
	v_fmac_f32_e32 v17, v16, v21
	global_store_dword v54, v17, s[12:13] nt
	v_fmac_f32_e32 v18, v17, v22
	global_store_dword v55, v18, s[12:13] nt
	v_fmac_f32_e32 v19, v18, v23
	v_mov_b32_e32 v4, v19
	v_add_u32_e32 v52, 0x8000, v52
	v_add_u32_e32 v53, 0x8000, v53
	v_add_u32_e32 v54, 0x8000, v54
	v_add_u32_e32 v55, 0x8000, v55
	global_load_dword v16, v48, s[10:11] nt
	global_load_dword v17, v49, s[10:11] nt
	global_load_dword v18, v50, s[10:11] nt
	global_load_dword v19, v51, s[10:11] nt
	global_load_dword v20, v0, s[0:1]
	global_load_dword v21, v0, s[0:1] offset:128
	global_load_dword v22, v0, s[0:1] offset:256
	global_load_dword v23, v0, s[0:1] offset:384
	v_add_u32_e32 v48, 0x8000, v48
	v_add_u32_e32 v49, 0x8000, v49
	v_add_u32_e32 v50, 0x8000, v50
	v_add_u32_e32 v51, 0x8000, v51
	v_add_u32_e32 v0, 0x200, v0
	s_waitcnt vmcnt(28)
	global_store_dword v52, v4, s[12:13] nt
	v_fmac_f32_e32 v24, v4, v28
	global_store_dword v53, v24, s[12:13] nt
	v_fmac_f32_e32 v25, v24, v29
	global_store_dword v54, v25, s[12:13] nt
	v_fmac_f32_e32 v26, v25, v30
	global_store_dword v55, v26, s[12:13] nt
	v_fmac_f32_e32 v27, v26, v31
	v_mov_b32_e32 v4, v27
	v_add_u32_e32 v52, 0x8000, v52
	v_add_u32_e32 v53, 0x8000, v53
	v_add_u32_e32 v54, 0x8000, v54
	v_add_u32_e32 v55, 0x8000, v55
	global_load_dword v24, v48, s[10:11] nt
	global_load_dword v25, v49, s[10:11] nt
	global_load_dword v26, v50, s[10:11] nt
	global_load_dword v27, v51, s[10:11] nt
	global_load_dword v28, v0, s[0:1]
	global_load_dword v29, v0, s[0:1] offset:128
	global_load_dword v30, v0, s[0:1] offset:256
	global_load_dword v31, v0, s[0:1] offset:384
	v_add_u32_e32 v48, 0x8000, v48
	v_add_u32_e32 v49, 0x8000, v49
	v_add_u32_e32 v50, 0x8000, v50
	v_add_u32_e32 v51, 0x8000, v51
	v_add_u32_e32 v0, 0x200, v0
	s_waitcnt vmcnt(32)
	global_store_dword v52, v4, s[12:13] nt
	v_fmac_f32_e32 v32, v4, v36
	global_store_dword v53, v32, s[12:13] nt
	v_fmac_f32_e32 v33, v32, v37
	global_store_dword v54, v33, s[12:13] nt
	v_fmac_f32_e32 v34, v33, v38
	global_store_dword v55, v34, s[12:13] nt
	v_fmac_f32_e32 v35, v34, v39
	v_mov_b32_e32 v4, v35
	v_add_u32_e32 v52, 0x8000, v52
	v_add_u32_e32 v53, 0x8000, v53
	v_add_u32_e32 v54, 0x8000, v54
	v_add_u32_e32 v55, 0x8000, v55
	global_load_dword v32, v48, s[10:11] nt
	global_load_dword v33, v49, s[10:11] nt
	global_load_dword v34, v50, s[10:11] nt
	global_load_dword v35, v51, s[10:11] nt
	global_load_dword v36, v0, s[0:1]
	global_load_dword v37, v0, s[0:1] offset:128
	global_load_dword v38, v0, s[0:1] offset:256
	global_load_dword v39, v0, s[0:1] offset:384
	v_add_u32_e32 v48, 0x8000, v48
	v_add_u32_e32 v49, 0x8000, v49
	v_add_u32_e32 v50, 0x8000, v50
	v_add_u32_e32 v51, 0x8000, v51
	v_add_u32_e32 v0, 0x200, v0
	s_waitcnt vmcnt(36)
	global_store_dword v52, v4, s[12:13] nt
	v_fmac_f32_e32 v40, v4, v44
	global_store_dword v53, v40, s[12:13] nt
	v_fmac_f32_e32 v41, v40, v45
	global_store_dword v54, v41, s[12:13] nt
	v_fmac_f32_e32 v42, v41, v46
	global_store_dword v55, v42, s[12:13] nt
	v_fmac_f32_e32 v43, v42, v47
	v_mov_b32_e32 v4, v43
	v_add_u32_e32 v52, 0x8000, v52
	v_add_u32_e32 v53, 0x8000, v53
	v_add_u32_e32 v54, 0x8000, v54
	v_add_u32_e32 v55, 0x8000, v55
	global_load_dword v40, v48, s[10:11] nt
	global_load_dword v41, v49, s[10:11] nt
	global_load_dword v42, v50, s[10:11] nt
	global_load_dword v43, v51, s[10:11] nt
	global_load_dword v44, v0, s[0:1]
	global_load_dword v45, v0, s[0:1] offset:128
	global_load_dword v46, v0, s[0:1] offset:256
	global_load_dword v47, v0, s[0:1] offset:384
	v_add_u32_e32 v48, 0x8000, v48
	v_add_u32_e32 v49, 0x8000, v49
	v_add_u32_e32 v50, 0x8000, v50
	v_add_u32_e32 v51, 0x8000, v51
	v_add_u32_e32 v0, 0x200, v0
	s_cmp_eq_u32 s14, 0
	s_cbranch_scc1 .Lscan_tail
; __device__ __forceinline__ void phase_gla_scan(const Params& p, int half, int bid, int nb) {
;     ...
;     float st = 0.f;
;     for (int n0 = 0; n0 < N; n0 += 8) {
;       float kv[8], dc[8];
; #pragma unroll
;       for (int u = 0; u < 8; ++u) {
;         kv[u] = __builtin_nontemporal_load(gkv + (base + n0 + u) * 2048 + e);
;         dc[u] = gdec[(base + n0 + u) * 32 + (e & 31)];
;       }
; #pragma unroll
;       for (int u = 0; u < 8; ++u) {
;         __builtin_nontemporal_store(st, gprev + (base + n0 + u) * 2048 + e);
;         st = dc[u] * st + kv[u];
;       }
;     }
.Lscan_grp:
	s_waitcnt vmcnt(36)
	global_store_dword v52, v4, s[12:13] nt
	v_fmac_f32_e32 v16, v4, v20
	global_store_dword v53, v16, s[12:13] nt
	v_fmac_f32_e32 v17, v16, v21
	global_store_dword v54, v17, s[12:13] nt
	v_fmac_f32_e32 v18, v17, v22
	global_store_dword v55, v18, s[12:13] nt
	v_fmac_f32_e32 v19, v18, v23
	v_mov_b32_e32 v4, v19
	v_add_u32_e32 v52, 0x8000, v52
	v_add_u32_e32 v53, 0x8000, v53
	v_add_u32_e32 v54, 0x8000, v54
	v_add_u32_e32 v55, 0x8000, v55
	global_load_dword v16, v48, s[10:11] nt
	global_load_dword v17, v49, s[10:11] nt
	global_load_dword v18, v50, s[10:11] nt
	global_load_dword v19, v51, s[10:11] nt
	global_load_dword v20, v0, s[0:1]
	global_load_dword v21, v0, s[0:1] offset:128
	global_load_dword v22, v0, s[0:1] offset:256
	global_load_dword v23, v0, s[0:1] offset:384
	v_add_u32_e32 v48, 0x8000, v48
	v_add_u32_e32 v49, 0x8000, v49
	v_add_u32_e32 v50, 0x8000, v50
	v_add_u32_e32 v51, 0x8000, v51
	v_add_u32_e32 v0, 0x200, v0
	s_waitcnt vmcnt(36)
	global_store_dword v52, v4, s[12:13] nt
	v_fmac_f32_e32 v24, v4, v28
	global_store_dword v53, v24, s[12:13] nt
	v_fmac_f32_e32 v25, v24, v29
	global_store_dword v54, v25, s[12:13] nt
	v_fmac_f32_e32 v26, v25, v30
	global_store_dword v55, v26, s[12:13] nt
	v_fmac_f32_e32 v27, v26, v31
	v_mov_b32_e32 v4, v27
	v_add_u32_e32 v52, 0x8000, v52
	v_add_u32_e32 v53, 0x8000, v53
	v_add_u32_e32 v54, 0x8000, v54
	v_add_u32_e32 v55, 0x8000, v55
	global_load_dword v24, v48, s[10:11] nt
	global_load_dword v25, v49, s[10:11] nt
	global_load_dword v26, v50, s[10:11] nt
	global_load_dword v27, v51, s[10:11] nt
	global_load_dword v28, v0, s[0:1]
	global_load_dword v29, v0, s[0:1] offset:128
	global_load_dword v30, v0, s[0:1] offset:256
	global_load_dword v31, v0, s[0:1] offset:384
	v_add_u32_e32 v48, 0x8000, v48
	v_add_u32_e32 v49, 0x8000, v49
	v_add_u32_e32 v50, 0x8000, v50
	v_add_u32_e32 v51, 0x8000, v51
	v_add_u32_e32 v0, 0x200, v0
	s_waitcnt vmcnt(36)
	global_store_dword v52, v4, s[12:13] nt
	v_fmac_f32_e32 v32, v4, v36
	global_store_dword v53, v32, s[12:13] nt
	v_fmac_f32_e32 v33, v32, v37
	global_store_dword v54, v33, s[12:13] nt
	v_fmac_f32_e32 v34, v33, v38
	global_store_dword v55, v34, s[12:13] nt
	v_fmac_f32_e32 v35, v34, v39
	v_mov_b32_e32 v4, v35
	v_add_u32_e32 v52, 0x8000, v52
	v_add_u32_e32 v53, 0x8000, v53
	v_add_u32_e32 v54, 0x8000, v54
	v_add_u32_e32 v55, 0x8000, v55
	global_load_dword v32, v48, s[10:11] nt
	global_load_dword v33, v49, s[10:11] nt
	global_load_dword v34, v50, s[10:11] nt
	global_load_dword v35, v51, s[10:11] nt
	global_load_dword v36, v0, s[0:1]
	global_load_dword v37, v0, s[0:1] offset:128
	global_load_dword v38, v0, s[0:1] offset:256
	global_load_dword v39, v0, s[0:1] offset:384
	v_add_u32_e32 v48, 0x8000, v48
	v_add_u32_e32 v49, 0x8000, v49
	v_add_u32_e32 v50, 0x8000, v50
	v_add_u32_e32 v51, 0x8000, v51
	v_add_u32_e32 v0, 0x200, v0
	s_waitcnt vmcnt(36)
	global_store_dword v52, v4, s[12:13] nt
	v_fmac_f32_e32 v40, v4, v44
	global_store_dword v53, v40, s[12:13] nt
	v_fmac_f32_e32 v41, v40, v45
	global_store_dword v54, v41, s[12:13] nt
	v_fmac_f32_e32 v42, v41, v46
	global_store_dword v55, v42, s[12:13] nt
	v_fmac_f32_e32 v43, v42, v47
	v_mov_b32_e32 v4, v43
	v_add_u32_e32 v52, 0x8000, v52
	v_add_u32_e32 v53, 0x8000, v53
	v_add_u32_e32 v54, 0x8000, v54
	v_add_u32_e32 v55, 0x8000, v55
	global_load_dword v40, v48, s[10:11] nt
	global_load_dword v41, v49, s[10:11] nt
	global_load_dword v42, v50, s[10:11] nt
	global_load_dword v43, v51, s[10:11] nt
	global_load_dword v44, v0, s[0:1]
	global_load_dword v45, v0, s[0:1] offset:128
	global_load_dword v46, v0, s[0:1] offset:256
	global_load_dword v47, v0, s[0:1] offset:384
	v_add_u32_e32 v48, 0x8000, v48
	v_add_u32_e32 v49, 0x8000, v49
	v_add_u32_e32 v50, 0x8000, v50
	v_add_u32_e32 v51, 0x8000, v51
	v_add_u32_e32 v0, 0x200, v0
	s_add_i32 s14, s14, -1
	s_cmp_lg_u32 s14, 0
	s_cbranch_scc1 .Lscan_grp
.Lscan_tail:
	s_waitcnt vmcnt(36)
	global_store_dword v52, v4, s[12:13] nt
	v_fmac_f32_e32 v16, v4, v20
	global_store_dword v53, v16, s[12:13] nt
	v_fmac_f32_e32 v17, v16, v21
	global_store_dword v54, v17, s[12:13] nt
	v_fmac_f32_e32 v18, v17, v22
	global_store_dword v55, v18, s[12:13] nt
	v_fmac_f32_e32 v19, v18, v23
	v_mov_b32_e32 v4, v19
	v_add_u32_e32 v52, 0x8000, v52
	v_add_u32_e32 v53, 0x8000, v53
	v_add_u32_e32 v54, 0x8000, v54
	v_add_u32_e32 v55, 0x8000, v55
	s_waitcnt vmcnt(28)
	global_store_dword v52, v4, s[12:13] nt
	v_fmac_f32_e32 v24, v4, v28
	global_store_dword v53, v24, s[12:13] nt
	v_fmac_f32_e32 v25, v24, v29
	global_store_dword v54, v25, s[12:13] nt
	v_fmac_f32_e32 v26, v25, v30
	global_store_dword v55, v26, s[12:13] nt
	v_fmac_f32_e32 v27, v26, v31
	v_mov_b32_e32 v4, v27
	v_add_u32_e32 v52, 0x8000, v52
	v_add_u32_e32 v53, 0x8000, v53
	v_add_u32_e32 v54, 0x8000, v54
	v_add_u32_e32 v55, 0x8000, v55
	s_waitcnt vmcnt(20)
	global_store_dword v52, v4, s[12:13] nt
	v_fmac_f32_e32 v32, v4, v36
	global_store_dword v53, v32, s[12:13] nt
	v_fmac_f32_e32 v33, v32, v37
	global_store_dword v54, v33, s[12:13] nt
	v_fmac_f32_e32 v34, v33, v38
	global_store_dword v55, v34, s[12:13] nt
	v_fmac_f32_e32 v35, v34, v39
	v_mov_b32_e32 v4, v35
	v_add_u32_e32 v52, 0x8000, v52
	v_add_u32_e32 v53, 0x8000, v53
	v_add_u32_e32 v54, 0x8000, v54
	v_add_u32_e32 v55, 0x8000, v55
	s_waitcnt vmcnt(12)
	global_store_dword v52, v4, s[12:13] nt
	v_fmac_f32_e32 v40, v4, v44
	global_store_dword v53, v40, s[12:13] nt
	v_fmac_f32_e32 v41, v40, v45
	global_store_dword v54, v41, s[12:13] nt
	v_fmac_f32_e32 v42, v41, v46
	global_store_dword v55, v42, s[12:13] nt
	v_fmac_f32_e32 v43, v42, v47
	v_mov_b32_e32 v4, v43
	v_add_u32_e32 v52, 0x8000, v52
	v_add_u32_e32 v53, 0x8000, v53
	v_add_u32_e32 v54, 0x8000, v54
	v_add_u32_e32 v55, 0x8000, v55
	v_readlane_b32 s10, v254, 46
	s_add_i32 s9, s9, s96
	s_add_i32 s8, s8, s10
	s_cmp_ge_i32 s9, s6
	s_cbranch_scc0 .LBB0_236

; __device__ __forceinline__ void gla_kv_job(const Params& p, int layer, int half, int job, char* smem) {
;     ...
;   {
;     int d = tid & 31, cg = tid >> 5;
; #pragma unroll
;     for (int cc = 0; cc < 8; ++cc) {
;       int c = cg * 8 + cc;
;       int pos = dir ? 63 - c : c;
;       kraw[cc] = proj[(size_t)(tok0 + pos) * PW + 128 + hd * 32 + d];
;     }
;     int v = tid & 63, cg2 = tid >> 6;
; #pragma unroll
;     for (int cc = 0; cc < 16; ++cc) {
;       int c = cg2 * 16 + cc;
;       int pos = dir ? 63 - c : c;
;       vv[cc] = proj[(size_t)(tok0 + pos) * PW + 256 + hd * 64 + v];
;     }
;   }
.LBB0_249:
	v_readlane_b32 s0, v255, 17
	s_mov_b32 s14, s66
	s_mov_b32 s11, s0
	v_mov_b32_e32 v0, v197
	s_cmp_eq_u32 s11, 0
	v_ashrrev_i32_e32 v12, 2, v0
	s_cselect_b64 s[12:13], -1, 0
	v_and_b32_e32 v14, -8, v12
	s_and_b64 s[20:21], s[12:13], exec
	v_readlane_b32 s40, v254, 40
	v_or_b32_e32 v15, 4, v14
	s_cselect_b32 s36, 32, 0x80
	s_ashr_i32 s37, s10, 3
	v_sub_u32_e32 v2, 63, v14
	v_readlane_b32 s41, v254, 41
	v_sub_u32_e32 v16, 63, v15
	s_lshl_b32 s15, s37, 6
	v_cndmask_b32_e64 v2, v2, v14, s[40:41]
	v_cndmask_b32_e64 v15, v16, v15, s[40:41]
	v_add_u32_e32 v4, s15, v2
	v_mov_b64_e32 v[2:3], s[6:7]
	v_add_u32_e32 v15, s15, v15
	v_mad_i64_i32 v[16:17], s[38:39], v15, s71, v[2:3]
	v_or_b32_e32 v15, 5, v14
	v_sub_u32_e32 v18, 63, v15
	v_cndmask_b32_e64 v15, v18, v15, s[40:41]
	s_bfe_u32 s11, s10, 0x20001
	v_add_u32_e32 v15, s15, v15
	v_and_b32_e32 v13, 31, v0
	s_lshl_b32 s66, s11, 6
	v_mad_i64_i32 v[18:19], s[38:39], v15, s71, v[2:3]
	v_lshlrev_b32_e32 v198, 1, v13
	v_lshl_add_u64 v[18:19], v[18:19], 0, s[66:67]
	v_or_b32_e32 v15, 6, v14
	v_lshl_add_u64 v[26:27], v[18:19], 0, v[198:199]
	v_sub_u32_e32 v18, 63, v15
	v_cndmask_b32_e64 v15, v18, v15, s[40:41]
	v_or_b32_e32 v6, 1, v14
	v_or_b32_e32 v8, 2, v14
	v_or_b32_e32 v10, 3, v14
	v_add_u32_e32 v15, s15, v15
	v_or_b32_e32 v33, 7, v12
	v_sub_u32_e32 v7, 63, v6
	v_sub_u32_e32 v9, 63, v8
	v_sub_u32_e32 v11, 63, v10
	v_mad_i64_i32 v[18:19], s[38:39], v15, s71, v[2:3]
	v_sub_u32_e32 v15, 63, v33
	v_cndmask_b32_e64 v6, v7, v6, s[40:41]
	v_cndmask_b32_e64 v8, v9, v8, s[40:41]
	v_cndmask_b32_e64 v10, v11, v10, s[40:41]
	v_cndmask_b32_e64 v15, v15, v33, s[40:41]
	v_mad_i64_i32 v[4:5], s[38:39], v4, s71, v[2:3]
	v_add_u32_e32 v6, s15, v6
	v_add_u32_e32 v8, s15, v8
	v_add_u32_e32 v10, s15, v10
	v_lshl_add_u64 v[18:19], v[18:19], 0, s[66:67]
	v_add_u32_e32 v15, s15, v15
	v_lshl_add_u64 v[4:5], v[4:5], 0, s[66:67]
	v_mad_i64_i32 v[6:7], s[38:39], v6, s71, v[2:3]
	v_mad_i64_i32 v[8:9], s[38:39], v8, s71, v[2:3]
	v_mad_i64_i32 v[10:11], s[38:39], v10, s71, v[2:3]
	v_lshl_add_u64 v[16:17], v[16:17], 0, s[66:67]
	v_lshl_add_u64 v[28:29], v[18:19], 0, v[198:199]
	v_mad_i64_i32 v[18:19], s[38:39], v15, s71, v[2:3]
	v_ashrrev_i32_e32 v1, 6, v0
	v_lshl_add_u64 v[4:5], v[4:5], 0, v[198:199]
	v_lshl_add_u64 v[6:7], v[6:7], 0, s[66:67]
	v_lshl_add_u64 v[8:9], v[8:9], 0, s[66:67]
	v_lshl_add_u64 v[10:11], v[10:11], 0, s[66:67]
	v_lshl_add_u64 v[16:17], v[16:17], 0, v[198:199]
	v_lshl_add_u64 v[18:19], v[18:19], 0, s[66:67]
	v_lshl_add_u64 v[6:7], v[6:7], 0, v[198:199]
	v_lshl_add_u64 v[8:9], v[8:9], 0, v[198:199]
	v_lshl_add_u64 v[10:11], v[10:11], 0, v[198:199]
	v_lshl_add_u64 v[30:31], v[18:19], 0, v[198:199]
	global_load_ushort v23, v[4:5], off offset:256
	global_load_ushort v24, v[6:7], off offset:256
	global_load_ushort v21, v[8:9], off offset:256
	global_load_ushort v22, v[10:11], off offset:256
	global_load_ushort v19, v[16:17], off offset:256
	global_load_ushort v20, v[26:27], off offset:256
	s_nop 0
	global_load_ushort v17, v[28:29], off offset:256
	global_load_ushort v18, v[30:31], off offset:256
	v_lshlrev_b32_e32 v16, 4, v1
	v_or_b32_e32 v25, 4, v16
	v_sub_u32_e32 v26, 63, v25
	v_cndmask_b32_e64 v25, v26, v25, s[40:41]
	v_add_u32_e32 v25, s15, v25
	v_and_b32_e32 v15, 63, v0
	s_lshl_b32 s66, s11, 7
	v_mad_i64_i32 v[26:27], s[38:39], v25, s71, v[2:3]
	v_lshlrev_b32_e32 v198, 1, v15
	v_lshl_add_u64 v[26:27], v[26:27], 0, s[66:67]
	v_or_b32_e32 v25, 5, v16
	v_lshl_add_u64 v[34:35], v[26:27], 0, v[198:199]
	v_sub_u32_e32 v26, 63, v25
	v_cndmask_b32_e64 v25, v26, v25, s[40:41]
	v_add_u32_e32 v25, s15, v25
	v_mad_i64_i32 v[26:27], s[38:39], v25, s71, v[2:3]
	v_lshl_add_u64 v[26:27], v[26:27], 0, s[66:67]
	v_or_b32_e32 v25, 6, v16
	v_lshl_add_u64 v[36:37], v[26:27], 0, v[198:199]
	v_sub_u32_e32 v26, 63, v25
	v_cndmask_b32_e64 v25, v26, v25, s[40:41]
	v_add_u32_e32 v25, s15, v25
	v_mad_i64_i32 v[26:27], s[38:39], v25, s71, v[2:3]
	v_sub_u32_e32 v4, 63, v16
	v_or_b32_e32 v6, 1, v16
	v_or_b32_e32 v8, 2, v16
	v_or_b32_e32 v10, 3, v16
	v_lshl_add_u64 v[26:27], v[26:27], 0, s[66:67]
	v_or_b32_e32 v25, 7, v16
	v_cndmask_b32_e64 v4, v4, v16, s[40:41]
	v_sub_u32_e32 v7, 63, v6
	v_sub_u32_e32 v9, 63, v8
	v_sub_u32_e32 v11, 63, v10
	v_lshl_add_u64 v[38:39], v[26:27], 0, v[198:199]
	v_sub_u32_e32 v26, 63, v25
	v_add_u32_e32 v4, s15, v4
	v_cndmask_b32_e64 v6, v7, v6, s[40:41]
	v_cndmask_b32_e64 v8, v9, v8, s[40:41]
	v_cndmask_b32_e64 v10, v11, v10, s[40:41]
	v_cndmask_b32_e64 v25, v26, v25, s[40:41]
	v_mad_i64_i32 v[4:5], s[38:39], v4, s71, v[2:3]
	v_add_u32_e32 v6, s15, v6
	v_add_u32_e32 v8, s15, v8
	v_add_u32_e32 v10, s15, v10
	v_add_u32_e32 v25, s15, v25
	v_lshl_add_u64 v[4:5], v[4:5], 0, s[66:67]
	v_mad_i64_i32 v[6:7], s[38:39], v6, s71, v[2:3]
	v_mad_i64_i32 v[8:9], s[38:39], v8, s71, v[2:3]
	v_mad_i64_i32 v[10:11], s[38:39], v10, s71, v[2:3]
	v_mad_i64_i32 v[26:27], s[38:39], v25, s71, v[2:3]
	v_lshl_add_u64 v[4:5], v[4:5], 0, v[198:199]
	v_lshl_add_u64 v[6:7], v[6:7], 0, s[66:67]
	v_lshl_add_u64 v[8:9], v[8:9], 0, s[66:67]
	v_lshl_add_u64 v[10:11], v[10:11], 0, s[66:67]
	v_lshl_add_u64 v[26:27], v[26:27], 0, s[66:67]
	v_lshl_add_u64 v[6:7], v[6:7], 0, v[198:199]
	v_lshl_add_u64 v[8:9], v[8:9], 0, v[198:199]
	v_lshl_add_u64 v[10:11], v[10:11], 0, v[198:199]
	v_lshl_add_u64 v[40:41], v[26:27], 0, v[198:199]
	global_load_ushort v25, v[4:5], off offset:512
	global_load_ushort v26, v[6:7], off offset:512
	global_load_ushort v28, v[8:9], off offset:512
	global_load_ushort v30, v[10:11], off offset:512
	global_load_ushort v27, v[34:35], off offset:512
	global_load_ushort v29, v[36:37], off offset:512
; __device__ __forceinline__ float bf2f(u16 h) { return __uint_as_float(((unsigned)h) << 16); }
; __device__ __forceinline__ void gla_prep_b(const Params& p, int layer, const u16* __restrict__ proj, int tok0, int hd, int dir,
;                            float* s_lr, float* s_b, float* s_tot) {
;     ...
;   {
;     int i = tid >> 2, q = tid & 3;
;     int pos = dir ? 63 - i : i;
;     uint2 v = *(const uint2*)(proj + (size_t)(tok0 + pos) * PW + 768 + dir * 16 + q * 4);
;     s_lr[i * 16 + q * 4 + 0] = bf2f((u16)(v.x & 0xffff));
;     s_lr[i * 16 + q * 4 + 1] = bf2f((u16)(v.x >> 16));
;     s_lr[i * 16 + q * 4 + 2] = bf2f((u16)(v.y & 0xffff));
;     s_lr[i * 16 + q * 4 + 3] = bf2f((u16)(v.y >> 16));
;   }
;   const int d = tid & 31, ig = tid >> 5;
;   const float* wgk = (dir ? p.gla_wgk_b : p.gla_wgk_f) + (size_t)layer * 16 * 128 + hd * 32 + d;
;   float wv[16];
; #pragma unroll
;   for (int r = 0; r < 16; ++r) wv[r] = wgk[r * 128];
;   const float bias = (dir ? p.gla_bgk_b : p.gla_bgk_f)[layer * 128 + hd * 32 + d];
;   __syncthreads();
; __device__ __forceinline__ void gla_kv_job(const Params& p, int layer, int half, int job, char* smem) {
;     ...
;     int v = tid & 63, cg2 = tid >> 6;
; #pragma unroll
;     for (int cc = 0; cc < 16; ++cc) {
;       int c = cg2 * 16 + cc;
;       int pos = dir ? 63 - c : c;
;       vv[cc] = proj[(size_t)(tok0 + pos) * PW + 256 + hd * 64 + v];
;     }
;   }
	global_load_ushort v31, v[38:39], off offset:512
	global_load_ushort v32, v[40:41], off offset:512
	v_or_b32_e32 v34, 12, v16
	v_sub_u32_e32 v35, 63, v34
	v_cndmask_b32_e64 v34, v35, v34, s[40:41]
	v_add_u32_e32 v34, s15, v34
	v_mad_i64_i32 v[34:35], s[38:39], v34, s71, v[2:3]
	v_lshl_add_u64 v[34:35], v[34:35], 0, s[66:67]
	v_lshl_add_u64 v[40:41], v[34:35], 0, v[198:199]
	v_or_b32_e32 v34, 13, v16
	v_sub_u32_e32 v35, 63, v34
	v_cndmask_b32_e64 v34, v35, v34, s[40:41]
	v_add_u32_e32 v34, s15, v34
	v_mad_i64_i32 v[34:35], s[38:39], v34, s71, v[2:3]
	v_lshl_add_u64 v[34:35], v[34:35], 0, s[66:67]
	v_lshl_add_u64 v[42:43], v[34:35], 0, v[198:199]
	v_or_b32_e32 v34, 14, v16
	v_sub_u32_e32 v35, 63, v34
	v_cndmask_b32_e64 v34, v35, v34, s[40:41]
	v_add_u32_e32 v34, s15, v34
	v_mad_i64_i32 v[34:35], s[38:39], v34, s71, v[2:3]
	v_or_b32_e32 v4, 8, v16
	v_lshl_add_u64 v[34:35], v[34:35], 0, s[66:67]
	v_sub_u32_e32 v5, 63, v4
	v_or_b32_e32 v6, 9, v16
	v_or_b32_e32 v8, 10, v16
	v_or_b32_e32 v10, 11, v16
	v_lshl_add_u64 v[44:45], v[34:35], 0, v[198:199]
	v_or_b32_e32 v34, 15, v16
	v_cndmask_b32_e64 v4, v5, v4, s[40:41]
	v_sub_u32_e32 v7, 63, v6
	v_sub_u32_e32 v9, 63, v8
	v_sub_u32_e32 v11, 63, v10
	v_sub_u32_e32 v35, 63, v34
	v_add_u32_e32 v4, s15, v4
	v_cndmask_b32_e64 v6, v7, v6, s[40:41]
	v_cndmask_b32_e64 v8, v9, v8, s[40:41]
	v_cndmask_b32_e64 v10, v11, v10, s[40:41]
	v_cndmask_b32_e64 v34, v35, v34, s[40:41]
	v_mad_i64_i32 v[4:5], s[38:39], v4, s71, v[2:3]
	v_add_u32_e32 v6, s15, v6
	v_add_u32_e32 v8, s15, v8
	v_add_u32_e32 v10, s15, v10
	v_add_u32_e32 v34, s15, v34
	v_lshl_add_u64 v[4:5], v[4:5], 0, s[66:67]
	v_mad_i64_i32 v[6:7], s[38:39], v6, s71, v[2:3]
	v_mad_i64_i32 v[8:9], s[38:39], v8, s71, v[2:3]
	v_mad_i64_i32 v[10:11], s[38:39], v10, s71, v[2:3]
	v_mad_i64_i32 v[2:3], s[38:39], v34, s71, v[2:3]
	v_lshl_add_u64 v[4:5], v[4:5], 0, v[198:199]
	v_lshl_add_u64 v[6:7], v[6:7], 0, s[66:67]
	v_lshl_add_u64 v[8:9], v[8:9], 0, s[66:67]
	v_lshl_add_u64 v[10:11], v[10:11], 0, s[66:67]
	v_lshl_add_u64 v[2:3], v[2:3], 0, s[66:67]
	v_lshl_add_u64 v[6:7], v[6:7], 0, v[198:199]
	v_lshl_add_u64 v[8:9], v[8:9], 0, v[198:199]
	v_lshl_add_u64 v[10:11], v[10:11], 0, v[198:199]
	v_lshl_add_u64 v[2:3], v[2:3], 0, v[198:199]
	global_load_ushort v34, v[4:5], off offset:512
	global_load_ushort v35, v[6:7], off offset:512
	global_load_ushort v37, v[8:9], off offset:512
	global_load_ushort v39, v[10:11], off offset:512
	global_load_ushort v36, v[40:41], off offset:512
	global_load_ushort v38, v[42:43], off offset:512
	s_nop 0
	global_load_ushort v40, v[44:45], off offset:512
	global_load_ushort v41, v[2:3], off offset:512
	v_mov_b32_e32 v42, v197
	s_lshl_b32 s20, s11, 5
	v_ashrrev_i32_e32 v45, 2, v42
	v_sub_u32_e32 v2, 63, v45
	v_cndmask_b32_e64 v2, v2, v45, s[40:41]
	v_lshlrev_b32_e32 v43, 2, v42
	v_add_u32_e32 v4, s15, v2
	v_mov_b64_e32 v[2:3], s[8:9]
	v_and_b32_e32 v47, 12, v43
	v_mad_i64_i32 v[2:3], s[38:39], v4, s71, v[2:3]
	v_lshlrev_b32_e32 v198, 1, v47
	v_lshl_add_u64 v[2:3], v[2:3], 0, v[198:199]
	s_ashr_i32 s15, s14, 31
	global_load_dwordx2 v[56:57], v[2:3], off offset:1536
	s_lshl_b64 s[38:39], s[14:15], 13
	s_add_u32 s15, s35, s38
	s_addc_u32 s21, s34, s39
	s_add_u32 s38, s15, s66
	s_addc_u32 s39, s21, 0
	s_lshl_b32 s14, s14, 7
	v_and_b32_e32 v44, 31, v42
	s_or_b32 s14, s14, s20
	v_or_b32_e32 v4, s14, v44
	v_ashrrev_i32_e32 v5, 31, v4
	v_lshl_add_u64 v[4:5], v[4:5], 2, s[2:3]
	v_lshlrev_b32_e32 v198, 2, v44
	global_load_dword v46, v[4:5], off
	global_load_dword v50, v198, s[38:39]
	global_load_dword v51, v198, s[38:39] offset:512
	global_load_dword v52, v198, s[38:39] offset:1024
	global_load_dword v53, v198, s[38:39] offset:1536
	global_load_dword v49, v198, s[38:39] offset:2048
	global_load_dword v48, v198, s[38:39] offset:2560
	global_load_dword v10, v198, s[38:39] offset:3072
	global_load_dword v11, v198, s[38:39] offset:3584
	v_lshl_add_u64 v[2:3], s[38:39], 0, v[198:199]
	s_movk_i32 s14, 0x1000
	v_add_co_u32_e32 v54, vcc, s14, v2
	v_lshlrev_b32_e32 v45, 6, v45
	s_nop 0
	v_addc_co_u32_e32 v55, vcc, 0, v3, vcc
	global_load_dword v8, v[54:55], off
	global_load_dword v9, v[54:55], off offset:512
	global_load_dword v6, v[54:55], off offset:1024
	global_load_dword v7, v[54:55], off offset:1536
	global_load_dword v4, v[54:55], off offset:2048
	global_load_dword v5, v[54:55], off offset:2560
	global_load_dword v2, v[54:55], off offset:3072
	global_load_dword v3, v[54:55], off offset:3584
	v_lshlrev_b32_e32 v47, 2, v47
	v_add3_u32 v45, s65, v45, v47
	v_ashrrev_i32_e32 v42, 5, v42
	s_mov_b32 s15, 0x3f2aaaab
	s_mov_b32 s20, 0x3f317218
	s_mov_b32 s21, 0x7f800000
	s_mov_b32 s38, 0x33800000
	s_mov_b32 s14, 0x3d800000
	v_readlane_b32 s1, v255, 18
	s_waitcnt vmcnt(0)
	v_lshlrev_b32_e32 v54, 16, v56
	v_and_b32_e32 v55, 0xffff0000, v56
	v_lshlrev_b32_e32 v56, 16, v57
	v_and_b32_e32 v57, 0xffff0000, v57
	ds_write_b128 v45, v[54:57]
	v_lshl_add_u32 v54, v42, 9, s65
	s_waitcnt lgkmcnt(0)
	s_barrier
; __device__ __forceinline__ void gla_prep_b(const Params& p, int layer, const u16* __restrict__ proj, int tok0, int hd, int dir,
;                            float* s_lr, float* s_b, float* s_tot) {
;     ...
;   float loc[8];
;   float run = 0.f;
; #pragma unroll
;   for (int ii = 0; ii < 8; ++ii) {
;     int i = ig * 8 + ii;
;     float z = bias;
; #pragma unroll
;     for (int r = 0; r < 16; ++r) z += s_lr[i * 16 + r] * wv[r];
;     float g = (fminf(z, 0.f) - log1pf(__expf(-fabsf(z)))) * (1.f / 16.f);
;     run += g;
;     loc[ii] = run;
;   }
	ds_read_b128 v[56:59], v54
	ds_read_b128 v[60:63], v54 offset:16
	ds_read_b128 v[64:67], v54 offset:32
	ds_read_b128 v[68:71], v54 offset:48
	s_waitcnt lgkmcnt(3)
	v_fma_f32 v45, v50, v56, v46
	v_fmac_f32_e32 v45, v51, v57
	v_fmac_f32_e32 v45, v52, v58
	v_fmac_f32_e32 v45, v53, v59
	s_waitcnt lgkmcnt(2)
	v_fmac_f32_e32 v45, v49, v60
	v_fmac_f32_e32 v45, v48, v61
	v_pk_mul_f32 v[56:57], v[10:11], v[62:63]
	s_nop 0
	v_add_f32_e32 v45, v45, v56
	v_add_f32_e32 v45, v45, v57
	s_waitcnt lgkmcnt(1)
	v_pk_mul_f32 v[56:57], v[8:9], v[64:65]
	s_nop 0
	v_add_f32_e32 v45, v45, v56
	v_add_f32_e32 v45, v45, v57
	v_pk_mul_f32 v[56:57], v[6:7], v[66:67]
	s_nop 0
	v_add_f32_e32 v45, v45, v56
	v_add_f32_e32 v45, v45, v57
	s_waitcnt lgkmcnt(0)
	v_pk_mul_f32 v[56:57], v[4:5], v[68:69]
	s_nop 0
	v_add_f32_e32 v45, v45, v56
	v_add_f32_e32 v45, v45, v57
	v_pk_mul_f32 v[56:57], v[2:3], v[70:71]
	s_nop 0
	v_add_f32_e32 v45, v45, v56
	v_add_f32_e32 v47, v45, v57
	v_mul_f32_e64 v45, |v47|, s62
	v_exp_f32_e32 v55, v45
	v_min_f32_e32 v47, 0, v47
	v_mov_b32_e32 v45, 0
	v_add_f32_e32 v58, 1.0, v55
	v_add_f32_e32 v56, -1.0, v58
	v_log_f32_e32 v60, v58
	v_rcp_f32_e32 v58, v56
	v_cmp_eq_f32_e32 vcc, 0, v56
	v_mul_f32_e32 v60, 0x3f317218, v60
	v_mul_f32_e32 v58, v55, v58
	v_mul_f32_e32 v60, v60, v58
	v_cndmask_b32_e32 v55, v60, v55, vcc
	s_nop 1
	s_nop 1
	s_nop 1
	ds_read_b128 v[56:59], v54 offset:64
	s_nop 1
	s_nop 1
	ds_read_b128 v[60:63], v54 offset:80
	s_waitcnt lgkmcnt(1)
	v_fma_f32 v64, v50, v56, v46
	v_fmac_f32_e32 v64, v51, v57
	v_fmac_f32_e32 v64, v52, v58
	v_fmac_f32_e32 v64, v53, v59
	ds_read_b128 v[56:59], v54 offset:96
	s_waitcnt lgkmcnt(1)
	v_fmac_f32_e32 v64, v49, v60
	v_fmac_f32_e32 v64, v48, v61
	v_pk_mul_f32 v[60:61], v[10:11], v[62:63]
	v_sub_f32_e32 v47, v47, v55
	v_add_f32_e32 v60, v64, v60
	v_add_f32_e32 v64, v60, v61
	ds_read_b128 v[60:63], v54 offset:112
	s_waitcnt lgkmcnt(1)
	v_pk_mul_f32 v[56:57], v[8:9], v[56:57]
	v_fma_f32 v47, v47, s14, 0
	v_add_f32_e32 v56, v64, v56
	v_add_f32_e32 v64, v56, v57
	v_pk_mul_f32 v[56:57], v[6:7], v[58:59]
	s_nop 0
	v_add_f32_e32 v56, v64, v56
	v_add_f32_e32 v58, v56, v57
	s_waitcnt lgkmcnt(0)
	v_pk_mul_f32 v[56:57], v[4:5], v[60:61]
	s_nop 0
	v_add_f32_e32 v56, v58, v56
	v_add_f32_e32 v58, v56, v57
	v_pk_mul_f32 v[56:57], v[2:3], v[62:63]
	s_nop 0
	v_add_f32_e32 v56, v58, v56
	v_add_f32_e32 v56, v56, v57
	v_mul_f32_e64 v57, |v56|, s62
	v_exp_f32_e32 v60, v57
	v_min_f32_e32 v55, 0, v56
	v_add_f32_e32 v58, 1.0, v60
	v_add_f32_e32 v56, -1.0, v58
	v_log_f32_e32 v61, v58
	v_rcp_f32_e32 v58, v56
	v_cmp_eq_f32_e32 vcc, 0, v56
	v_mul_f32_e32 v61, 0x3f317218, v61
	v_mul_f32_e32 v58, v60, v58
	v_mul_f32_e32 v61, v61, v58
	v_cndmask_b32_e32 v64, v61, v60, vcc
	s_nop 1
	s_nop 1
	s_nop 1
	ds_read_b128 v[56:59], v54 offset:128
	s_nop 1
	s_nop 1
	ds_read_b128 v[60:63], v54 offset:144
	s_waitcnt lgkmcnt(1)
	v_fma_f32 v65, v50, v56, v46
	v_fmac_f32_e32 v65, v51, v57
	v_fmac_f32_e32 v65, v52, v58
	v_fmac_f32_e32 v65, v53, v59
	ds_read_b128 v[56:59], v54 offset:160
	s_waitcnt lgkmcnt(1)
	v_fmac_f32_e32 v65, v49, v60
	v_fmac_f32_e32 v65, v48, v61
	v_pk_mul_f32 v[60:61], v[10:11], v[62:63]
	v_sub_f32_e32 v55, v55, v64
	v_add_f32_e32 v60, v65, v60
	v_add_f32_e32 v65, v60, v61
	ds_read_b128 v[60:63], v54 offset:176
	s_waitcnt lgkmcnt(1)
	v_pk_mul_f32 v[56:57], v[8:9], v[56:57]
	v_fmamk_f32 v55, v55, 0x3d800000, v47
	v_add_f32_e32 v56, v65, v56
	v_add_f32_e32 v65, v56, v57
	v_pk_mul_f32 v[56:57], v[6:7], v[58:59]
	s_nop 0
	v_add_f32_e32 v56, v65, v56
	v_add_f32_e32 v58, v56, v57
	s_waitcnt lgkmcnt(0)
	v_pk_mul_f32 v[56:57], v[4:5], v[60:61]
	s_nop 0
	v_add_f32_e32 v56, v58, v56
	v_add_f32_e32 v58, v56, v57
	v_pk_mul_f32 v[56:57], v[2:3], v[62:63]
	s_nop 0
	v_add_f32_e32 v56, v58, v56
	v_add_f32_e32 v56, v56, v57
	v_mul_f32_e64 v57, |v56|, s62
	v_exp_f32_e32 v60, v57
	v_min_f32_e32 v64, 0, v56
	v_add_f32_e32 v58, 1.0, v60
	v_add_f32_e32 v56, -1.0, v58
	v_log_f32_e32 v61, v58
	v_rcp_f32_e32 v58, v56
	v_cmp_eq_f32_e32 vcc, 0, v56
	v_mul_f32_e32 v61, 0x3f317218, v61
	v_mul_f32_e32 v58, v60, v58
	v_mul_f32_e32 v61, v61, v58
	v_cndmask_b32_e32 v65, v61, v60, vcc
	s_nop 1
	s_nop 1
	s_nop 1
	ds_read_b128 v[56:59], v54 offset:192
	s_nop 1
	s_nop 1
	ds_read_b128 v[60:63], v54 offset:208
	s_waitcnt lgkmcnt(1)
	v_fma_f32 v66, v50, v56, v46
	v_fmac_f32_e32 v66, v51, v57
	v_fmac_f32_e32 v66, v52, v58
	v_fmac_f32_e32 v66, v53, v59
	ds_read_b128 v[56:59], v54 offset:224
	s_waitcnt lgkmcnt(1)
	v_fmac_f32_e32 v66, v49, v60
	v_fmac_f32_e32 v66, v48, v61
	v_pk_mul_f32 v[60:61], v[10:11], v[62:63]
	s_nop 0
	v_add_f32_e32 v60, v66, v60
	v_add_f32_e32 v66, v60, v61
	ds_read_b128 v[60:63], v54 offset:240
	s_waitcnt lgkmcnt(1)
	v_pk_mul_f32 v[56:57], v[8:9], v[56:57]
	s_nop 0
	v_add_f32_e32 v56, v66, v56
	v_add_f32_e32 v66, v56, v57
	v_pk_mul_f32 v[56:57], v[6:7], v[58:59]
	s_nop 0
	v_add_f32_e32 v56, v66, v56
	v_add_f32_e32 v58, v56, v57
	s_waitcnt lgkmcnt(0)
	v_pk_mul_f32 v[56:57], v[4:5], v[60:61]
	s_nop 0
	v_add_f32_e32 v56, v58, v56
	v_add_f32_e32 v58, v56, v57
	v_pk_mul_f32 v[56:57], v[2:3], v[62:63]
	s_nop 0
	v_add_f32_e32 v56, v58, v56
	v_add_f32_e32 v57, v56, v57
	v_mul_f32_e64 v56, |v57|, s62
	v_exp_f32_e32 v62, v56
	v_sub_f32_e32 v56, v64, v65
	v_min_f32_e32 v57, 0, v57
	v_fmamk_f32 v56, v56, 0x3d800000, v55
	v_add_f32_e32 v60, 1.0, v62
	v_add_f32_e32 v58, -1.0, v60
	v_log_f32_e32 v63, v60
	v_rcp_f32_e32 v60, v58
	v_cmp_eq_f32_e32 vcc, 0, v58
	v_mul_f32_e32 v63, 0x3f317218, v63
	v_mul_f32_e32 v60, v62, v60
	v_mul_f32_e32 v63, v63, v60
	v_cndmask_b32_e32 v66, v63, v62, vcc
	s_nop 1
	s_nop 1
	s_nop 1
	ds_read_b128 v[58:61], v54 offset:256
	s_nop 1
	s_nop 1
	ds_read_b128 v[62:65], v54 offset:272
	s_waitcnt lgkmcnt(1)
; __device__ __forceinline__ void gla_prep_b(const Params& p, int layer, const u16* __restrict__ proj, int tok0, int hd, int dir,
;                            float* s_lr, float* s_b, float* s_tot) {
;     ...
; #pragma unroll
;   for (int ii = 0; ii < 8; ++ii) {
;     int i = ig * 8 + ii;
;     float z = bias;
; #pragma unroll
;     for (int r = 0; r < 16; ++r) z += s_lr[i * 16 + r] * wv[r];
;     float g = (fminf(z, 0.f) - log1pf(__expf(-fabsf(z)))) * (1.f / 16.f);
;     run += g;
;     loc[ii] = run;
;   }
;   s_tot[ig * 32 + d] = run;
;   __syncthreads();
;   float off = 0.f;
;   for (int g2 = 0; g2 < ig; ++g2) off += s_tot[g2 * 32 + d];
	v_fma_f32 v67, v50, v58, v46
	v_fmac_f32_e32 v67, v51, v59
	v_fmac_f32_e32 v67, v52, v60
	v_fmac_f32_e32 v67, v53, v61
	ds_read_b128 v[58:61], v54 offset:288
	s_waitcnt lgkmcnt(1)
	v_fmac_f32_e32 v67, v49, v62
	v_fmac_f32_e32 v67, v48, v63
	v_pk_mul_f32 v[62:63], v[10:11], v[64:65]
	v_sub_f32_e32 v57, v57, v66
	v_add_f32_e32 v62, v67, v62
	v_add_f32_e32 v67, v62, v63
	ds_read_b128 v[62:65], v54 offset:304
	s_waitcnt lgkmcnt(1)
	v_pk_mul_f32 v[58:59], v[8:9], v[58:59]
	v_fmamk_f32 v57, v57, 0x3d800000, v56
	v_add_f32_e32 v58, v67, v58
	v_add_f32_e32 v67, v58, v59
	v_pk_mul_f32 v[58:59], v[6:7], v[60:61]
	s_nop 0
	v_add_f32_e32 v58, v67, v58
	v_add_f32_e32 v60, v58, v59
	s_waitcnt lgkmcnt(0)
	v_pk_mul_f32 v[58:59], v[4:5], v[62:63]
	s_nop 0
	v_add_f32_e32 v58, v60, v58
	v_add_f32_e32 v60, v58, v59
	v_pk_mul_f32 v[58:59], v[2:3], v[64:65]
	s_nop 0
	v_add_f32_e32 v58, v60, v58
	v_add_f32_e32 v58, v58, v59
	v_mul_f32_e64 v59, |v58|, s62
	v_exp_f32_e32 v62, v59
	v_min_f32_e32 v66, 0, v58
	v_add_f32_e32 v60, 1.0, v62
	v_add_f32_e32 v58, -1.0, v60
	v_log_f32_e32 v63, v60
	v_rcp_f32_e32 v60, v58
	v_cmp_eq_f32_e32 vcc, 0, v58
	v_mul_f32_e32 v63, 0x3f317218, v63
	v_mul_f32_e32 v60, v62, v60
	v_mul_f32_e32 v63, v63, v60
	v_cndmask_b32_e32 v67, v63, v62, vcc
	s_nop 1
	s_nop 1
	s_nop 1
	ds_read_b128 v[58:61], v54 offset:320
	s_nop 1
	s_nop 1
	ds_read_b128 v[62:65], v54 offset:336
	s_waitcnt lgkmcnt(1)
	v_fma_f32 v68, v50, v58, v46
	v_fmac_f32_e32 v68, v51, v59
	v_fmac_f32_e32 v68, v52, v60
	v_fmac_f32_e32 v68, v53, v61
	ds_read_b128 v[58:61], v54 offset:352
	s_waitcnt lgkmcnt(1)
	v_fmac_f32_e32 v68, v49, v62
	v_fmac_f32_e32 v68, v48, v63
	v_pk_mul_f32 v[62:63], v[10:11], v[64:65]
	s_nop 0
	v_add_f32_e32 v62, v68, v62
	v_add_f32_e32 v68, v62, v63
	ds_read_b128 v[62:65], v54 offset:368
	s_waitcnt lgkmcnt(1)
	v_pk_mul_f32 v[58:59], v[8:9], v[58:59]
	s_nop 0
	v_add_f32_e32 v58, v68, v58
	v_add_f32_e32 v68, v58, v59
	v_pk_mul_f32 v[58:59], v[6:7], v[60:61]
	s_nop 0
	v_add_f32_e32 v58, v68, v58
	v_add_f32_e32 v60, v58, v59
	s_waitcnt lgkmcnt(0)
	v_pk_mul_f32 v[58:59], v[4:5], v[62:63]
	s_nop 0
	v_add_f32_e32 v58, v60, v58
	v_add_f32_e32 v60, v58, v59
	v_pk_mul_f32 v[58:59], v[2:3], v[64:65]
	s_nop 0
	v_add_f32_e32 v58, v60, v58
	v_add_f32_e32 v59, v58, v59
	v_mul_f32_e64 v58, |v59|, s62
	v_exp_f32_e32 v64, v58
	v_sub_f32_e32 v58, v66, v67
	v_min_f32_e32 v59, 0, v59
	v_fmamk_f32 v58, v58, 0x3d800000, v57
	v_add_f32_e32 v62, 1.0, v64
	v_add_f32_e32 v60, -1.0, v62
	v_log_f32_e32 v65, v62
	v_rcp_f32_e32 v62, v60
	v_cmp_eq_f32_e32 vcc, 0, v60
	v_mul_f32_e32 v65, 0x3f317218, v65
	v_mul_f32_e32 v62, v64, v62
	v_mul_f32_e32 v65, v65, v62
	v_cndmask_b32_e32 v68, v65, v64, vcc
	s_nop 1
	s_nop 1
	s_nop 1
	ds_read_b128 v[60:63], v54 offset:384
	s_nop 1
	s_nop 1
	ds_read_b128 v[64:67], v54 offset:400
	s_waitcnt lgkmcnt(1)
	v_fma_f32 v69, v50, v60, v46
	v_fmac_f32_e32 v69, v51, v61
	v_fmac_f32_e32 v69, v52, v62
	v_fmac_f32_e32 v69, v53, v63
	ds_read_b128 v[60:63], v54 offset:416
	s_waitcnt lgkmcnt(1)
	v_fmac_f32_e32 v69, v49, v64
	v_fmac_f32_e32 v69, v48, v65
	v_pk_mul_f32 v[64:65], v[10:11], v[66:67]
	v_sub_f32_e32 v59, v59, v68
	v_add_f32_e32 v64, v69, v64
	v_add_f32_e32 v69, v64, v65
	ds_read_b128 v[64:67], v54 offset:432
	s_waitcnt lgkmcnt(1)
	v_pk_mul_f32 v[60:61], v[8:9], v[60:61]
	v_fmamk_f32 v59, v59, 0x3d800000, v58
	v_add_f32_e32 v60, v69, v60
	v_add_f32_e32 v69, v60, v61
	v_pk_mul_f32 v[60:61], v[6:7], v[62:63]
	s_nop 0
	v_add_f32_e32 v60, v69, v60
	v_add_f32_e32 v62, v60, v61
	s_waitcnt lgkmcnt(0)
	v_pk_mul_f32 v[60:61], v[4:5], v[64:65]
	s_nop 0
	v_add_f32_e32 v60, v62, v60
	v_add_f32_e32 v62, v60, v61
	v_pk_mul_f32 v[60:61], v[2:3], v[66:67]
	s_nop 0
	v_add_f32_e32 v60, v62, v60
	v_add_f32_e32 v60, v60, v61
	v_mul_f32_e64 v61, |v60|, s62
	v_exp_f32_e32 v64, v61
	v_min_f32_e32 v68, 0, v60
	v_add_f32_e32 v62, 1.0, v64
	v_add_f32_e32 v60, -1.0, v62
	v_log_f32_e32 v65, v62
	v_rcp_f32_e32 v62, v60
	v_cmp_eq_f32_e32 vcc, 0, v60
	v_mul_f32_e32 v65, 0x3f317218, v65
	v_mul_f32_e32 v62, v64, v62
	v_mul_f32_e32 v65, v65, v62
	v_cndmask_b32_e32 v69, v65, v64, vcc
	s_nop 1
	s_nop 1
	s_nop 1
	ds_read_b128 v[60:63], v54 offset:448
	s_nop 1
	s_nop 1
	ds_read_b128 v[64:67], v54 offset:464
	s_waitcnt lgkmcnt(1)
	v_fmac_f32_e32 v46, v50, v60
	v_fmac_f32_e32 v46, v51, v61
	v_fmac_f32_e32 v46, v52, v62
	v_fmac_f32_e32 v46, v53, v63
	s_waitcnt lgkmcnt(0)
	v_fmac_f32_e32 v46, v49, v64
	v_fmac_f32_e32 v46, v48, v65
	ds_read_b128 v[48:51], v54 offset:480
	ds_read_b128 v[60:63], v54 offset:496
	v_pk_mul_f32 v[10:11], v[10:11], v[66:67]
	s_waitcnt lgkmcnt(1)
	v_pk_mul_f32 v[8:9], v[8:9], v[48:49]
	v_add_f32_e32 v10, v46, v10
	v_add_f32_e32 v10, v10, v11
	v_add_f32_e32 v8, v10, v8
	v_add_f32_e32 v8, v8, v9
	v_pk_mul_f32 v[6:7], v[6:7], v[50:51]
	s_waitcnt lgkmcnt(0)
	v_pk_mul_f32 v[4:5], v[4:5], v[60:61]
	v_add_f32_e32 v6, v8, v6
	v_add_f32_e32 v6, v6, v7
	v_add_f32_e32 v4, v6, v4
	v_add_f32_e32 v4, v4, v5
	v_pk_mul_f32 v[2:3], v[2:3], v[62:63]
	s_nop 0
	v_add_f32_e32 v2, v4, v2
	v_add_f32_e32 v3, v2, v3
	v_mul_f32_e64 v2, |v3|, s62
	v_exp_f32_e32 v6, v2
	v_sub_f32_e32 v2, v68, v69
	v_min_f32_e32 v3, 0, v3
	v_fmamk_f32 v2, v2, 0x3d800000, v59
	v_add_f32_e32 v7, 1.0, v6
	v_add_f32_e32 v4, -1.0, v7
	v_log_f32_e32 v9, v7
	v_rcp_f32_e32 v7, v4
	v_cmp_eq_f32_e32 vcc, 0, v4
	v_mul_f32_e32 v9, 0x3f317218, v9
	v_mul_f32_e32 v7, v6, v7
	v_mul_f32_e32 v9, v9, v7
	v_cndmask_b32_e32 v4, v9, v6, vcc
	s_nop 1
	s_nop 1
	s_nop 1
	s_nop 1
	s_nop 1
	v_sub_f32_e32 v3, v3, v4
	v_fmamk_f32 v3, v3, 0x3d800000, v2
	v_add_u32_e32 v4, s65, v43
	v_cmp_lt_i32_e32 vcc, 0, v42
	ds_write_b32 v4, v3 offset:12544
	s_waitcnt lgkmcnt(0)
	s_barrier
	s_and_saveexec_b64 s[14:15], vcc
	s_cbranch_execz .LBB0_253
	v_readlane_b32 s20, v254, 49
	v_mov_b32_e32 v45, 0
	v_mov_b32_e32 v5, v42
	v_lshl_add_u32 v4, v44, 2, s20
	s_mov_b64 s[20:21], 0
